# G1: next unit's 16 input loads (glrp partials + q/k/v fragments) issued one unit ahead into idle VGPRs; units 1..3 copy instead of load
# baseline (speedup 1.0000x reference)
.LBB0_1090:
	s_or_b32 s8, s87, s81
	s_bfe_i32 s0, s8, 0x1e0000
	s_ashr_i32 s1, s0, 31
	s_lshl_b64 s[10:11], s[0:1], 12
	v_lshl_add_u64 v[66:67], v[116:117], 0, s[10:11]
	v_add_co_u32_e32 v68, vcc, s33, v66
	s_lshl_b64 s[0:1], s[0:1], 17
	s_nop 0
	v_addc_co_u32_e32 v69, vcc, 0, v67, vcc
	v_add_co_u32_e32 v70, vcc, s55, v66
	v_mov_b32_e32 v124, v0
	s_nop 0
	v_addc_co_u32_e32 v71, vcc, 0, v67, vcc
	v_add_co_u32_e32 v72, vcc, s70, v66
	s_nop 1
	v_addc_co_u32_e32 v73, vcc, 0, v67, vcc
	s_cmp_eq_u32 s87, 0
	s_cbranch_scc0 .Lg1_copy
	global_load_dword v98, v[66:67], off
	global_load_dword v99, v[68:69], off
	global_load_dword v100, v[70:71], off
	global_load_dword v101, v[72:73], off
	global_load_dword v102, v[72:73], off offset:2048
	global_load_dword v103, v[70:71], off offset:2048
	global_load_dword v104, v[68:69], off offset:2048
	global_load_dword v105, v[66:67], off offset:2048
	v_lshl_or_b32 v66, v118, 1, s0
	v_mov_b32_e32 v67, s1
	v_lshl_add_u64 v[68:69], v[120:121], 0, v[66:67]
	v_lshl_add_u64 v[70:71], v[122:123], 0, v[66:67]
	global_load_dwordx4 v[94:97], v[68:69], off
	global_load_dwordx4 v[90:93], v[68:69], off offset:1024
	global_load_dwordx4 v[86:89], v[68:69], off offset:2048
	global_load_dwordx4 v[82:85], v[68:69], off offset:3072
	global_load_dwordx4 v[74:77], v[70:71], off
	s_nop 0
	global_load_dwordx4 v[66:69], v[70:71], off offset:256
	global_load_dwordx4 v[78:81], v[70:71], off offset:2048
	s_nop 0
	global_load_dwordx4 v[70:73], v[70:71], off offset:2304
	s_waitcnt vmcnt(8)
	s_branch .Lg1_in
.Lg1_copy:
	s_waitcnt vmcnt(14)
	v_mov_b32_e32 v98, v190
	v_mov_b32_e32 v99, v191
	v_mov_b32_e32 v100, v192
	v_mov_b32_e32 v101, v193
	v_mov_b32_e32 v102, v194
	v_mov_b32_e32 v103, v195
	v_mov_b32_e32 v104, v196
	v_mov_b32_e32 v105, v197
	v_mov_b64_e32 v[94:95], v[204:205]
	v_mov_b64_e32 v[96:97], v[206:207]
	v_mov_b64_e32 v[90:91], v[208:209]
	v_mov_b64_e32 v[92:93], v[210:211]
	v_mov_b64_e32 v[86:87], v[212:213]
	v_mov_b64_e32 v[88:89], v[214:215]
	v_mov_b64_e32 v[82:83], v[216:217]
	v_mov_b64_e32 v[84:85], v[218:219]
	v_mov_b64_e32 v[74:75], v[220:221]
	v_mov_b64_e32 v[76:77], v[222:223]
	v_mov_b64_e32 v[66:67], v[224:225]
	v_mov_b64_e32 v[68:69], v[226:227]
	v_mov_b64_e32 v[78:79], v[228:229]
	v_mov_b64_e32 v[80:81], v[230:231]
	v_mov_b64_e32 v[70:71], v[232:233]
	v_mov_b64_e32 v[72:73], v[234:235]

.LBB0_1096:
	s_or_b64 exec, exec, s[0:1]
	s_waitcnt vmcnt(5)
	v_and_b32_e32 v84, 0xffff, v74
	v_add3_u32 v82, 0, v83, v82
	v_lshrrev_b32_e32 v74, 16, v74
	s_waitcnt vmcnt(3)
	v_lshl_or_b32 v84, v78, 16, v84
	v_add_u32_e32 v82, 0xd000, v82
	v_and_or_b32 v74, v78, s82, v74
	s_waitcnt lgkmcnt(0)
	s_barrier
	ds_write2_b32 v82, v84, v74 offset1:36
	v_and_b32_e32 v74, 0xffff, v75
	v_lshrrev_b32_e32 v75, 16, v75
	v_lshl_or_b32 v74, v79, 16, v74
	v_and_or_b32 v75, v79, s82, v75
	ds_write2_b32 v82, v74, v75 offset0:72 offset1:108
	v_and_b32_e32 v74, 0xffff, v76
	v_lshrrev_b32_e32 v75, 16, v76
	v_lshl_or_b32 v74, v80, 16, v74
	v_and_or_b32 v75, v80, s82, v75
	ds_write2_b32 v82, v74, v75 offset0:144 offset1:180
	v_and_b32_e32 v74, 0xffff, v77
	v_lshrrev_b32_e32 v75, 16, v77
	v_lshl_or_b32 v74, v81, 16, v74
	v_and_or_b32 v75, v81, s82, v75
	ds_write2_b32 v82, v74, v75 offset0:216 offset1:252
	v_and_b32_e32 v74, 0xffff, v66
	v_lshrrev_b32_e32 v66, 16, v66
	s_waitcnt vmcnt(2)
	v_lshl_or_b32 v74, v70, 16, v74
	v_and_or_b32 v66, v70, s82, v66
	v_add_u32_e32 v70, 0x4800, v82
	ds_write2_b32 v70, v74, v66 offset1:36
	v_and_b32_e32 v66, 0xffff, v67
	v_lshrrev_b32_e32 v67, 16, v67
	v_lshl_or_b32 v66, v71, 16, v66
	v_and_or_b32 v67, v71, s82, v67
	ds_write2_b32 v70, v66, v67 offset0:72 offset1:108
	v_and_b32_e32 v66, 0xffff, v68
	v_lshrrev_b32_e32 v67, 16, v68
	v_lshl_or_b32 v66, v72, 16, v66
	v_and_or_b32 v67, v72, s82, v67
	ds_write2_b32 v70, v66, v67 offset0:144 offset1:180
	v_and_b32_e32 v66, 0xffff, v69
	v_lshrrev_b32_e32 v67, 16, v69
	v_lshl_or_b32 v66, v73, 16, v66
	v_and_or_b32 v67, v73, s82, v67
	s_bfe_u32 s88, s17, 0x10006
	ds_write2_b32 v70, v66, v67 offset0:216 offset1:252
	v_lshl_or_b32 v66, s88, 5, v156
	v_mad_u32_u24 v66, v66, s84, 0
	v_lshlrev_b32_e32 v126, 4, v158
	v_add_u32_e32 v103, v66, v126
	v_mad_u32_u24 v66, v156, s84, 0
	s_cmp_lt_u32 s87, 3
	s_cbranch_scc0 .Lg1_nopf
	s_or_b32 s100, s87, s81
	s_add_i32 s100, s100, 1
	s_bfe_i32 s100, s100, 0x1e0000
	s_ashr_i32 s101, s100, 31
	s_lshl_b64 s[100:101], s[100:101], 12
	v_lshl_add_u64 v[236:237], v[116:117], 0, s[100:101]
	v_mov_b32_e32 v244, s33
	v_mov_b32_e32 v245, 0
	v_lshl_add_u64 v[238:239], v[236:237], 0, v[244:245]
	v_mov_b32_e32 v244, s55
	v_lshl_add_u64 v[240:241], v[236:237], 0, v[244:245]
	v_mov_b32_e32 v244, s70
	v_lshl_add_u64 v[242:243], v[236:237], 0, v[244:245]
	global_load_dword v190, v[236:237], off
	global_load_dword v191, v[238:239], off
	global_load_dword v192, v[240:241], off
	global_load_dword v193, v[242:243], off
	global_load_dword v194, v[242:243], off offset:2048
	global_load_dword v195, v[240:241], off offset:2048
	global_load_dword v196, v[238:239], off offset:2048
	global_load_dword v197, v[236:237], off offset:2048
	s_lshl_b64 s[100:101], s[100:101], 5
	v_lshl_or_b32 v236, v118, 1, s100
	v_mov_b32_e32 v237, s101
	v_lshl_add_u64 v[238:239], v[120:121], 0, v[236:237]
	v_lshl_add_u64 v[240:241], v[122:123], 0, v[236:237]
	global_load_dwordx4 v[204:207], v[238:239], off
	global_load_dwordx4 v[208:211], v[238:239], off offset:1024
	global_load_dwordx4 v[212:215], v[238:239], off offset:2048
	global_load_dwordx4 v[216:219], v[238:239], off offset:3072
	global_load_dwordx4 v[220:223], v[240:241], off
	global_load_dwordx4 v[224:227], v[240:241], off offset:256
	global_load_dwordx4 v[228:231], v[240:241], off offset:2048
	global_load_dwordx4 v[232:235], v[240:241], off offset:2304
.Lg1_nopf:
	s_waitcnt lgkmcnt(0)
	s_barrier
	v_add_u32_e32 v102, v66, v126
	ds_read_b128 v[98:101], v103
	ds_read_b128 v[66:69], v102 offset:17408
	s_waitcnt lgkmcnt(0)
	v_mfma_f32_32x32x16_bf16 v[66:81], v[66:69], v[98:101], 0
	s_mov_b32 s30, s16
	s_mov_b32 s31, s16
	s_bitcmp1_b32 s17, 6
	s_mov_b32 s17, s16
	s_mov_b32 s18, s16
	s_mov_b32 s19, s16
	s_mov_b32 s20, s16
	s_mov_b32 s21, s16
	s_mov_b32 s22, s16
	s_mov_b32 s23, s16
	s_mov_b32 s24, s16
	s_mov_b32 s25, s16
	s_mov_b32 s26, s16
	s_mov_b32 s27, s16
	s_mov_b32 s28, s16
	s_mov_b32 s29, s16
	v_mov_b64_e32 v[96:97], s[30:31]
	s_cselect_b64 s[10:11], -1, 0
	s_cmp_eq_u32 s88, 0
	v_mov_b64_e32 v[94:95], s[28:29]
	v_mov_b64_e32 v[92:93], s[26:27]
	v_mov_b64_e32 v[90:91], s[24:25]
	v_mov_b64_e32 v[88:89], s[22:23]
	v_mov_b64_e32 v[86:87], s[20:21]
	v_mov_b64_e32 v[84:85], s[18:19]
	v_mov_b64_e32 v[82:83], s[16:17]
	s_cbranch_scc1 .LBB0_1098
	ds_read_b128 v[82:85], v102 offset:26112
	s_waitcnt lgkmcnt(0)
	v_mfma_f32_32x32x16_bf16 v[82:97], v[82:85], v[98:101], 0
